# UP last round split: the 6th unit of each CU is a half-unit (128 rows) shared with the previously idle CU of the same team
# baseline (speedup 1.0000x reference)
.LBB0_562:
	s_add_i32 s44, s44, 1
	s_mov_b32 s32, 0
	s_cmp_eq_u32 s44, 6
	s_cbranch_scc0 .Lup_nohalf
	v_readlane_b32 s32, v254, 29
	s_lshr_b32 s32, s32, 7
	s_sub_i32 s32, 2, s32
.Lup_nohalf:
	v_readlane_b32 s22, v255, 15
	s_mul_i32 s19, s44, s33
	v_readlane_b32 s23, v255, 16
	s_mul_hi_u32 s21, s44, s22
	s_add_i32 s21, s21, s19
	s_mul_i32 s19, s44, s22
	v_readlane_b32 s22, v254, 29
	v_readlane_b32 s23, v254, 30
	s_add_u32 s22, s19, s22
	s_addc_u32 s23, s21, s23
	s_cmp_lt_u32 s22, 0x580
	s_cbranch_scc1 .Lup_Lok
	s_sub_u32 s22, s22, 0x80
.Lup_Lok:
	s_nop 0
	v_cmp_gt_i64_e32 vcc, s[22:23], v[206:207]
	v_cmp_lt_i64_e64 s[36:37], s[22:23], v[204:205]
	s_cbranch_vccnz .LBB0_564
	s_ashr_i32 s18, s22, 31
	s_lshr_b32 s18, s18, 29
	s_add_i32 s18, s22, s18
	s_ashr_i32 s19, s18, 3
	s_and_b32 s18, s18, -8
	s_sub_i32 s18, s22, s18
	s_cmp_lt_i32 s18, 0
	s_movk_i32 s20, 0xb1
	s_cselect_b32 s20, s20, 0xb0
	s_mul_i32 s18, s18, s20
	s_add_i32 s18, s18, s19
	s_mul_hi_i32 s19, s18, 0x2e8ba2e9
	s_lshr_b32 s20, s19, 31
	s_ashr_i32 s19, s19, 5
	s_add_i32 s19, s19, s20
	s_lshl_b32 s20, s19, 3
	s_sub_i32 s21, 64, s20
	s_min_i32 s21, s21, 8
	s_abs_i32 s22, s21
	v_cvt_f32_u32_e32 v0, s22
	s_sub_i32 s30, 0, s22
	s_mulk_i32 s19, 0xb0
	s_sub_i32 s19, s18, s19
	v_rcp_iflag_f32_e32 v0, v0
	s_abs_i32 s18, s19
	s_xor_b32 s23, s19, s21
	s_ashr_i32 s23, s23, 31
	v_mul_f32_e32 v0, 0x4f7ffffe, v0
	v_cvt_u32_f32_e32 v0, v0
	s_nop 0
	v_readfirstlane_b32 s31, v0
	s_mul_i32 s30, s30, s31
	s_mul_hi_u32 s30, s31, s30
	s_add_i32 s31, s31, s30
	s_mul_hi_u32 s30, s18, s31
	s_mul_i32 s31, s30, s22
	s_sub_i32 s18, s18, s31
	s_add_i32 s42, s30, 1
	s_sub_i32 s31, s18, s22
	s_cmp_ge_u32 s18, s22
	s_cselect_b32 s30, s42, s30
	s_cselect_b32 s18, s31, s18
	s_add_i32 s31, s30, 1
	s_cmp_ge_u32 s18, s22
	s_cselect_b32 s18, s31, s30
	s_xor_b32 s18, s18, s23
	s_sub_i32 s18, s18, s23
	s_mul_i32 s21, s18, s21
	s_sub_i32 s19, s19, s21
	s_add_i32 s20, s20, s19

.LBB0_565:
	s_add_u32 s40, s38, 0xfffc0080
	s_addc_u32 s41, s39, -1
	s_add_i32 s52, 0, 0x10000
	s_cmp_eq_u32 s51, 12
	s_cselect_b32 s43, s21, s41
	s_cselect_b32 s42, s47, s40
	v_add_u32_e32 v0, s52, v141
	s_cselect_b32 s41, s19, s50
	s_cselect_b32 s40, s48, s49
	s_add_i32 s54, 0, 0x14000
	ds_read_b128 v[146:149], v0
	ds_read_b128 v[150:153], v0 offset:1024
	ds_read_b128 v[154:157], v0 offset:2048
	ds_read_b128 v[158:161], v0 offset:3072
	v_add_u32_e32 v0, s54, v141
	ds_read_b128 v[162:165], v0
	ds_read_b128 v[166:169], v0 offset:1024
	ds_read_b128 v[170:173], v0 offset:2048
	ds_read_b128 v[174:177], v0 offset:3072
	v_lshl_add_u64 v[220:221], s[38:39], 0, v[138:139]
	s_add_i32 m0, s8, 0xc000
	ds_read_b128 v[178:181], v145
	ds_read_b128 v[182:185], v145 offset:1024
	ds_read_b128 v[186:189], v145 offset:2048
	ds_read_b128 v[190:193], v145 offset:3072
	ds_read_b128 v[194:197], v145 offset:4096
	ds_read_b128 v[208:211], v145 offset:5120
	ds_read_b128 v[212:215], v145 offset:6144
	ds_read_b128 v[216:219], v145 offset:7168
	global_load_lds_dwordx4 v[220:221], off
	v_lshl_add_u64 v[220:221], s[38:39], 0, v[136:137]
	s_add_i32 m0, s8, 0xe000
	s_nop 0
	global_load_lds_dwordx4 v[220:221], off
	s_waitcnt vmcnt(8)
	s_waitcnt lgkmcnt(0)
	s_barrier
	s_cmp_eq_u32 s32, 1
	s_cbranch_scc1 .Lup_sk0
	s_setprio 1
	s_waitcnt lgkmcnt(0)
	v_mfma_f32_16x16x32_bf16 v[130:133], v[146:149], v[178:181], v[130:133]
	v_mfma_f32_16x16x32_bf16 v[126:129], v[154:157], v[178:181], v[126:129]
	v_mfma_f32_16x16x32_bf16 v[114:117], v[146:149], v[186:189], v[114:117]
	v_mfma_f32_16x16x32_bf16 v[110:113], v[154:157], v[186:189], v[110:113]
	v_mfma_f32_16x16x32_bf16 v[98:101], v[146:149], v[194:197], v[98:101]
	v_mfma_f32_16x16x32_bf16 v[90:93], v[154:157], v[194:197], v[90:93]
	v_mfma_f32_16x16x32_bf16 v[78:81], v[146:149], v[212:215], v[78:81]
	v_mfma_f32_16x16x32_bf16 v[74:77], v[154:157], v[212:215], v[74:77]
	v_mfma_f32_16x16x32_bf16 v[130:133], v[150:153], v[182:185], v[130:133]
	v_mfma_f32_16x16x32_bf16 v[126:129], v[158:161], v[182:185], v[126:129]
	v_mfma_f32_16x16x32_bf16 v[114:117], v[150:153], v[190:193], v[114:117]
	v_mfma_f32_16x16x32_bf16 v[110:113], v[158:161], v[190:193], v[110:113]
	v_mfma_f32_16x16x32_bf16 v[98:101], v[150:153], v[208:211], v[98:101]
	v_mfma_f32_16x16x32_bf16 v[90:93], v[158:161], v[208:211], v[90:93]
	v_mfma_f32_16x16x32_bf16 v[78:81], v[150:153], v[216:219], v[78:81]
	v_mfma_f32_16x16x32_bf16 v[74:77], v[158:161], v[216:219], v[74:77]
	s_setprio 0
	s_setprio 1
	v_mfma_f32_16x16x32_bf16 v[122:125], v[162:165], v[178:181], v[122:125]
	v_mfma_f32_16x16x32_bf16 v[118:121], v[170:173], v[178:181], v[118:121]
	v_mfma_f32_16x16x32_bf16 v[106:109], v[162:165], v[186:189], v[106:109]
	v_mfma_f32_16x16x32_bf16 v[102:105], v[170:173], v[186:189], v[102:105]
	v_mfma_f32_16x16x32_bf16 v[86:89], v[162:165], v[194:197], v[86:89]
	v_mfma_f32_16x16x32_bf16 v[82:85], v[170:173], v[194:197], v[82:85]
	v_mfma_f32_16x16x32_bf16 v[70:73], v[162:165], v[212:215], v[70:73]
	v_mfma_f32_16x16x32_bf16 v[66:69], v[170:173], v[212:215], v[66:69]
	v_mfma_f32_16x16x32_bf16 v[122:125], v[166:169], v[182:185], v[122:125]
	v_mfma_f32_16x16x32_bf16 v[118:121], v[174:177], v[182:185], v[118:121]
	v_mfma_f32_16x16x32_bf16 v[106:109], v[166:169], v[190:193], v[106:109]
	v_mfma_f32_16x16x32_bf16 v[102:105], v[174:177], v[190:193], v[102:105]
	v_mfma_f32_16x16x32_bf16 v[86:89], v[166:169], v[208:211], v[86:89]
	v_mfma_f32_16x16x32_bf16 v[82:85], v[174:177], v[208:211], v[82:85]
	v_mfma_f32_16x16x32_bf16 v[70:73], v[166:169], v[216:219], v[70:73]
	v_mfma_f32_16x16x32_bf16 v[66:69], v[174:177], v[216:219], v[66:69]
	s_setprio 0
.Lup_sk0:
	s_barrier
	s_add_i32 s52, s52, s6
	v_lshl_add_u64 v[220:221], s[40:41], 0, v[134:135]
	s_mov_b32 m0, s52
	ds_read_b128 v[178:181], v145 offset:16384
	ds_read_b128 v[182:185], v145 offset:17408
	ds_read_b128 v[186:189], v145 offset:18432
	ds_read_b128 v[190:193], v145 offset:19456
	ds_read_b128 v[194:197], v145 offset:20480
	ds_read_b128 v[208:211], v145 offset:21504
	ds_read_b128 v[212:215], v145 offset:22528
	ds_read_b128 v[216:219], v145 offset:23552
	global_load_lds_dwordx4 v[220:221], off
	s_add_i32 m0, s52, 0x2000
	s_add_u32 s52, s40, 0x40000
	v_lshl_add_u64 v[232:233], s[40:41], 0, v[94:95]
	s_addc_u32 s53, s41, 0
	s_add_i32 s54, s54, s6
	global_load_lds_dwordx4 v[232:233], off
	v_lshl_add_u64 v[234:235], s[52:53], 0, v[134:135]
	s_mov_b32 m0, s54
	v_lshl_add_u64 v[236:237], s[42:43], 0, v[94:95]
	global_load_lds_dwordx4 v[234:235], off
	v_lshl_add_u64 v[234:235], s[52:53], 0, v[94:95]
	s_add_i32 m0, s54, 0x2000
	s_nop 0
	global_load_lds_dwordx4 v[234:235], off
	v_lshl_add_u64 v[234:235], s[42:43], 0, v[134:135]
	s_mov_b32 m0, s8
	s_nop 0
	global_load_lds_dwordx4 v[234:235], off
	s_mov_b32 m0, s9
	s_nop 0
	global_load_lds_dwordx4 v[236:237], off
	s_waitcnt vmcnt(8)
	s_waitcnt lgkmcnt(0)
	s_barrier
	s_cmp_eq_u32 s32, 2
	s_cbranch_scc1 .Lup_sk1
	s_setprio 1
	s_waitcnt lgkmcnt(0)
	v_mfma_f32_16x16x32_bf16 v[62:65], v[146:149], v[178:181], v[62:65]
	v_mfma_f32_16x16x32_bf16 v[58:61], v[154:157], v[178:181], v[58:61]
	v_mfma_f32_16x16x32_bf16 v[46:49], v[146:149], v[186:189], v[46:49]
	v_mfma_f32_16x16x32_bf16 v[42:45], v[154:157], v[186:189], v[42:45]
	v_mfma_f32_16x16x32_bf16 v[30:33], v[146:149], v[194:197], v[30:33]
	v_mfma_f32_16x16x32_bf16 v[26:29], v[154:157], v[194:197], v[26:29]
	v_mfma_f32_16x16x32_bf16 v[14:17], v[146:149], v[212:215], v[14:17]
	v_mfma_f32_16x16x32_bf16 v[10:13], v[154:157], v[212:215], v[10:13]
	v_mfma_f32_16x16x32_bf16 v[62:65], v[150:153], v[182:185], v[62:65]
	v_mfma_f32_16x16x32_bf16 v[58:61], v[158:161], v[182:185], v[58:61]
	v_mfma_f32_16x16x32_bf16 v[46:49], v[150:153], v[190:193], v[46:49]
	v_mfma_f32_16x16x32_bf16 v[42:45], v[158:161], v[190:193], v[42:45]
	v_mfma_f32_16x16x32_bf16 v[30:33], v[150:153], v[208:211], v[30:33]
	v_mfma_f32_16x16x32_bf16 v[26:29], v[158:161], v[208:211], v[26:29]
	v_mfma_f32_16x16x32_bf16 v[14:17], v[150:153], v[216:219], v[14:17]
	v_mfma_f32_16x16x32_bf16 v[10:13], v[158:161], v[216:219], v[10:13]
	s_setprio 0
	s_setprio 1
	v_mfma_f32_16x16x32_bf16 v[54:57], v[162:165], v[178:181], v[54:57]
	v_mfma_f32_16x16x32_bf16 v[50:53], v[170:173], v[178:181], v[50:53]
	v_mfma_f32_16x16x32_bf16 v[38:41], v[162:165], v[186:189], v[38:41]
	v_mfma_f32_16x16x32_bf16 v[34:37], v[170:173], v[186:189], v[34:37]
	v_mfma_f32_16x16x32_bf16 v[22:25], v[162:165], v[194:197], v[22:25]
	v_mfma_f32_16x16x32_bf16 v[18:21], v[170:173], v[194:197], v[18:21]
	v_mfma_f32_16x16x32_bf16 v[6:9], v[162:165], v[212:215], v[6:9]
	v_mfma_f32_16x16x32_bf16 v[2:5], v[170:173], v[212:215], v[2:5]
	v_mfma_f32_16x16x32_bf16 v[54:57], v[166:169], v[182:185], v[54:57]
	v_mfma_f32_16x16x32_bf16 v[50:53], v[174:177], v[182:185], v[50:53]
	v_mfma_f32_16x16x32_bf16 v[38:41], v[166:169], v[190:193], v[38:41]
	v_mfma_f32_16x16x32_bf16 v[34:37], v[174:177], v[190:193], v[34:37]
	v_mfma_f32_16x16x32_bf16 v[22:25], v[166:169], v[208:211], v[22:25]
	v_mfma_f32_16x16x32_bf16 v[18:21], v[174:177], v[208:211], v[18:21]
	v_mfma_f32_16x16x32_bf16 v[6:9], v[166:169], v[216:219], v[6:9]
	v_mfma_f32_16x16x32_bf16 v[2:5], v[174:177], v[216:219], v[2:5]
	s_setprio 0
.Lup_sk1:
	s_barrier
	s_add_i32 s52, 0, 0x18000
	v_add_u32_e32 v0, s52, v141
	s_add_i32 s53, 0, 0x1c000
	ds_read_b128 v[146:149], v0
	ds_read_b128 v[150:153], v0 offset:1024
	ds_read_b128 v[154:157], v0 offset:2048
	ds_read_b128 v[158:161], v0 offset:3072
	v_add_u32_e32 v0, s53, v141
	ds_read_b128 v[162:165], v0
	ds_read_b128 v[166:169], v0 offset:1024
	ds_read_b128 v[170:173], v0 offset:2048
	ds_read_b128 v[174:177], v0 offset:3072
	s_add_u32 s42, s42, 0x40000
	s_addc_u32 s43, s43, 0
	s_mov_b32 m0, s12
	v_lshl_add_u64 v[238:239], s[42:43], 0, v[134:135]
	ds_read_b128 v[178:181], v145 offset:32768
	ds_read_b128 v[182:185], v145 offset:33792
	ds_read_b128 v[186:189], v145 offset:34816
	ds_read_b128 v[190:193], v145 offset:35840
	ds_read_b128 v[194:197], v145 offset:36864
	ds_read_b128 v[208:211], v145 offset:37888
	ds_read_b128 v[212:215], v145 offset:38912
	ds_read_b128 v[216:219], v145 offset:39936
	global_load_lds_dwordx4 v[238:239], off
	v_lshl_add_u64 v[238:239], s[42:43], 0, v[94:95]
	s_mov_b32 m0, s13
	s_nop 0
	global_load_lds_dwordx4 v[238:239], off
	s_waitcnt vmcnt(8)
	s_waitcnt lgkmcnt(0)
	s_barrier
	s_cmp_eq_u32 s32, 1
	s_cbranch_scc1 .Lup_sk2
	s_setprio 1
	s_waitcnt lgkmcnt(0)
	v_mfma_f32_16x16x32_bf16 v[130:133], v[146:149], v[178:181], v[130:133]
	v_mfma_f32_16x16x32_bf16 v[126:129], v[154:157], v[178:181], v[126:129]
	v_mfma_f32_16x16x32_bf16 v[114:117], v[146:149], v[186:189], v[114:117]
	v_mfma_f32_16x16x32_bf16 v[110:113], v[154:157], v[186:189], v[110:113]
	v_mfma_f32_16x16x32_bf16 v[98:101], v[146:149], v[194:197], v[98:101]
	v_mfma_f32_16x16x32_bf16 v[90:93], v[154:157], v[194:197], v[90:93]
	v_mfma_f32_16x16x32_bf16 v[78:81], v[146:149], v[212:215], v[78:81]
	v_mfma_f32_16x16x32_bf16 v[74:77], v[154:157], v[212:215], v[74:77]
	v_mfma_f32_16x16x32_bf16 v[130:133], v[150:153], v[182:185], v[130:133]
	v_mfma_f32_16x16x32_bf16 v[126:129], v[158:161], v[182:185], v[126:129]
	v_mfma_f32_16x16x32_bf16 v[114:117], v[150:153], v[190:193], v[114:117]
	v_mfma_f32_16x16x32_bf16 v[110:113], v[158:161], v[190:193], v[110:113]
	v_mfma_f32_16x16x32_bf16 v[98:101], v[150:153], v[208:211], v[98:101]
	v_mfma_f32_16x16x32_bf16 v[90:93], v[158:161], v[208:211], v[90:93]
	v_mfma_f32_16x16x32_bf16 v[78:81], v[150:153], v[216:219], v[78:81]
	v_mfma_f32_16x16x32_bf16 v[74:77], v[158:161], v[216:219], v[74:77]
	s_setprio 0
	s_setprio 1
	v_mfma_f32_16x16x32_bf16 v[122:125], v[162:165], v[178:181], v[122:125]
	v_mfma_f32_16x16x32_bf16 v[118:121], v[170:173], v[178:181], v[118:121]
	v_mfma_f32_16x16x32_bf16 v[106:109], v[162:165], v[186:189], v[106:109]
	v_mfma_f32_16x16x32_bf16 v[102:105], v[170:173], v[186:189], v[102:105]
	v_mfma_f32_16x16x32_bf16 v[86:89], v[162:165], v[194:197], v[86:89]
	v_mfma_f32_16x16x32_bf16 v[82:85], v[170:173], v[194:197], v[82:85]
	v_mfma_f32_16x16x32_bf16 v[70:73], v[162:165], v[212:215], v[70:73]
	v_mfma_f32_16x16x32_bf16 v[66:69], v[170:173], v[212:215], v[66:69]
	v_mfma_f32_16x16x32_bf16 v[122:125], v[166:169], v[182:185], v[122:125]
	v_mfma_f32_16x16x32_bf16 v[118:121], v[174:177], v[182:185], v[118:121]
	v_mfma_f32_16x16x32_bf16 v[106:109], v[166:169], v[190:193], v[106:109]
	v_mfma_f32_16x16x32_bf16 v[102:105], v[174:177], v[190:193], v[102:105]
	v_mfma_f32_16x16x32_bf16 v[86:89], v[166:169], v[208:211], v[86:89]
	v_mfma_f32_16x16x32_bf16 v[82:85], v[174:177], v[208:211], v[82:85]
	v_mfma_f32_16x16x32_bf16 v[70:73], v[166:169], v[216:219], v[70:73]
	v_mfma_f32_16x16x32_bf16 v[66:69], v[174:177], v[216:219], v[66:69]
	s_setprio 0
.Lup_sk2:
	s_barrier
	s_add_i32 s42, s52, s6
	v_lshl_add_u64 v[220:221], v[220:221], 0, s[34:35]
	s_mov_b32 m0, s42
	ds_read_b128 v[178:181], v145 offset:49152
	ds_read_b128 v[182:185], v145 offset:50176
	ds_read_b128 v[186:189], v145 offset:51200
	ds_read_b128 v[190:193], v145 offset:52224
	ds_read_b128 v[194:197], v145 offset:53248
	ds_read_b128 v[208:211], v145 offset:54272
	ds_read_b128 v[212:215], v145 offset:55296
	ds_read_b128 v[216:219], v145 offset:56320
	global_load_lds_dwordx4 v[220:221], off
	s_add_i32 m0, s42, 0x2000
	s_add_u32 s40, s40, 0x40080
	v_lshl_add_u64 v[220:221], v[232:233], 0, s[34:35]
	s_addc_u32 s41, s41, 0
	s_add_i32 s42, s53, s6
	global_load_lds_dwordx4 v[220:221], off
	v_lshl_add_u64 v[220:221], s[40:41], 0, v[134:135]
	s_mov_b32 m0, s42
	s_nop 0
	global_load_lds_dwordx4 v[220:221], off
	v_lshl_add_u64 v[220:221], s[40:41], 0, v[94:95]
	s_add_i32 m0, s42, 0x2000
	s_nop 0
	global_load_lds_dwordx4 v[220:221], off
	v_lshl_add_u64 v[220:221], v[234:235], 0, s[34:35]
	s_mov_b32 m0, s28
	s_nop 0
	global_load_lds_dwordx4 v[220:221], off
	v_lshl_add_u64 v[220:221], v[236:237], 0, s[34:35]
	s_mov_b32 m0, s29
	s_nop 0
	global_load_lds_dwordx4 v[220:221], off
	s_waitcnt vmcnt(8)
	s_waitcnt lgkmcnt(0)
	s_barrier
	s_cmp_eq_u32 s32, 2
	s_cbranch_scc1 .Lup_sk3
	s_setprio 1
	s_waitcnt lgkmcnt(0)
	v_mfma_f32_16x16x32_bf16 v[62:65], v[146:149], v[178:181], v[62:65]
	v_mfma_f32_16x16x32_bf16 v[58:61], v[154:157], v[178:181], v[58:61]
	v_mfma_f32_16x16x32_bf16 v[46:49], v[146:149], v[186:189], v[46:49]
	v_mfma_f32_16x16x32_bf16 v[42:45], v[154:157], v[186:189], v[42:45]
	v_mfma_f32_16x16x32_bf16 v[30:33], v[146:149], v[194:197], v[30:33]
	v_mfma_f32_16x16x32_bf16 v[26:29], v[154:157], v[194:197], v[26:29]
	v_mfma_f32_16x16x32_bf16 v[14:17], v[146:149], v[212:215], v[14:17]
	v_mfma_f32_16x16x32_bf16 v[10:13], v[154:157], v[212:215], v[10:13]
	v_mfma_f32_16x16x32_bf16 v[62:65], v[150:153], v[182:185], v[62:65]
	v_mfma_f32_16x16x32_bf16 v[58:61], v[158:161], v[182:185], v[58:61]
	v_mfma_f32_16x16x32_bf16 v[46:49], v[150:153], v[190:193], v[46:49]
	v_mfma_f32_16x16x32_bf16 v[42:45], v[158:161], v[190:193], v[42:45]
	v_mfma_f32_16x16x32_bf16 v[30:33], v[150:153], v[208:211], v[30:33]
	v_mfma_f32_16x16x32_bf16 v[26:29], v[158:161], v[208:211], v[26:29]
	v_mfma_f32_16x16x32_bf16 v[14:17], v[150:153], v[216:219], v[14:17]
	v_mfma_f32_16x16x32_bf16 v[10:13], v[158:161], v[216:219], v[10:13]
	s_setprio 0
	s_setprio 1
	v_mfma_f32_16x16x32_bf16 v[54:57], v[162:165], v[178:181], v[54:57]
	v_mfma_f32_16x16x32_bf16 v[50:53], v[170:173], v[178:181], v[50:53]
	v_mfma_f32_16x16x32_bf16 v[38:41], v[162:165], v[186:189], v[38:41]
	v_mfma_f32_16x16x32_bf16 v[34:37], v[170:173], v[186:189], v[34:37]
	v_mfma_f32_16x16x32_bf16 v[22:25], v[162:165], v[194:197], v[22:25]
	v_mfma_f32_16x16x32_bf16 v[18:21], v[170:173], v[194:197], v[18:21]
	v_mfma_f32_16x16x32_bf16 v[6:9], v[162:165], v[212:215], v[6:9]
	v_mfma_f32_16x16x32_bf16 v[2:5], v[170:173], v[212:215], v[2:5]
	v_mfma_f32_16x16x32_bf16 v[54:57], v[166:169], v[182:185], v[54:57]
	v_mfma_f32_16x16x32_bf16 v[50:53], v[174:177], v[182:185], v[50:53]
	v_mfma_f32_16x16x32_bf16 v[38:41], v[166:169], v[190:193], v[38:41]
	v_mfma_f32_16x16x32_bf16 v[34:37], v[174:177], v[190:193], v[34:37]
	v_mfma_f32_16x16x32_bf16 v[22:25], v[166:169], v[208:211], v[22:25]
	v_mfma_f32_16x16x32_bf16 v[18:21], v[174:177], v[208:211], v[18:21]
	v_mfma_f32_16x16x32_bf16 v[6:9], v[166:169], v[216:219], v[6:9]
	v_mfma_f32_16x16x32_bf16 v[2:5], v[174:177], v[216:219], v[2:5]
	s_setprio 0
.Lup_sk3:
	s_barrier
	s_add_i32 s51, s51, 2
	s_add_u32 s49, s49, 0x100
	s_addc_u32 s50, s50, 0
	s_add_u32 s38, s38, 0x100
	s_addc_u32 s39, s39, 0
	s_cmp_gt_u32 s51, 13
	s_cbranch_scc0 .LBB0_565
	s_and_b64 vcc, exec, s[10:11]
	s_cbranch_vccz .LBB0_568
	s_barrier
.LBB0_568:
	s_lshl_b32 s19, s46, 8
	s_add_i32 s19, s19, s25
	v_or_b32_e32 v146, s19, v97
	v_or_b32_e32 v148, 16, v146
	v_or_b32_e32 v150, 32, v146
	v_ashrrev_i32_e32 v149, 31, v148
	v_ashrrev_i32_e32 v151, 31, v150
	v_lshl_add_u64 v[148:149], v[148:149], 4, s[16:17]
	v_lshl_add_u64 v[156:157], v[150:151], 4, s[16:17]
	global_load_dwordx4 v[150:153], v[148:149], off
	s_nop 0
	global_load_dwordx4 v[156:159], v[156:157], off
	v_or_b32_e32 v148, 48, v146
	v_ashrrev_i32_e32 v149, 31, v148
	v_lshl_add_u64 v[160:161], v[148:149], 4, s[16:17]
	v_add_u32_e32 v148, 0x80, v146
	v_ashrrev_i32_e32 v147, 31, v146
	v_ashrrev_i32_e32 v149, 31, v148
	v_lshl_add_u64 v[154:155], v[146:147], 4, s[16:17]
	v_lshl_add_u64 v[146:147], v[148:149], 4, s[16:17]
	global_load_dwordx4 v[160:163], v[160:161], off
	s_nop 0
	global_load_dwordx4 v[164:167], v[146:147], off
	global_load_dwordx4 v[168:171], v[154:155], off
	global_load_dwordx4 v[172:175], v[154:155], off offset:2304
	global_load_dwordx4 v[176:179], v[154:155], off offset:2560
	global_load_dwordx4 v[180:183], v[154:155], off offset:2816
	v_lshl_or_b32 v184, s45, 7, v143
	s_waitcnt vmcnt(0)
	v_mov_b32_e32 v146, v169
	v_mov_b32_e32 v147, v170
	v_mov_b32_e32 v169, v171
	v_pk_add_f32 v[146:147], v[146:147], v[168:169]
	s_ashr_i32 s21, s19, 11
	v_add_f32_e32 v0, v146, v147
	v_mov_b32_e32 v146, v151
	v_mov_b32_e32 v147, v152
	v_mov_b32_e32 v151, v153
	v_pk_add_f32 v[146:147], v[146:147], v[150:151]
	v_fmamk_f32 v0, v0, 0x3a800000, v222
	v_add_f32_e32 v140, v146, v147
	v_mov_b32_e32 v146, v157
	v_mov_b32_e32 v147, v158
	v_mov_b32_e32 v157, v159
	v_rsq_f32_e32 v0, v0
	v_fmamk_f32 v140, v140, 0x3a800000, v222
	v_pk_add_f32 v[146:147], v[146:147], v[156:157]
	v_rsq_f32_e32 v154, v140
	v_add_f32_e32 v140, v146, v147
	v_mov_b32_e32 v146, v161
	v_mov_b32_e32 v147, v162
	v_mov_b32_e32 v161, v163
	v_fmamk_f32 v140, v140, 0x3a800000, v222
	v_pk_add_f32 v[146:147], v[146:147], v[160:161]
	v_rsq_f32_e32 v152, v140
	v_add_f32_e32 v140, v146, v147
	v_mov_b32_e32 v146, v165
	v_mov_b32_e32 v147, v166
	v_mov_b32_e32 v165, v167
	v_fmamk_f32 v140, v140, 0x3a800000, v222
	v_pk_add_f32 v[146:147], v[146:147], v[164:165]
	v_pk_mul_f32 v[130:131], v[130:131], v[0:1] op_sel_hi:[1,0]
	v_rsq_f32_e32 v150, v140
	v_add_f32_e32 v140, v146, v147
	v_mov_b32_e32 v156, v173
	v_mov_b32_e32 v157, v174
	v_mov_b32_e32 v173, v175
	v_mul_f32_e32 v151, 0xbfb8aa3b, v131
	v_fmamk_f32 v140, v140, 0x3a800000, v222
	v_pk_add_f32 v[156:157], v[156:157], v[172:173]
	v_mul_f32_e32 v147, 0xbfb8aa3b, v130
	v_exp_f32_e32 v151, v151
	v_rsq_f32_e32 v146, v140
	v_add_f32_e32 v140, v156, v157
	v_mov_b32_e32 v156, v177
	v_mov_b32_e32 v157, v178
	v_mov_b32_e32 v177, v179
	v_exp_f32_e32 v147, v147
	v_fmamk_f32 v140, v140, 0x3a800000, v222
	v_pk_add_f32 v[156:157], v[156:157], v[176:177]
	v_rsq_f32_e32 v144, v140
	v_add_f32_e32 v140, v156, v157
	v_mov_b32_e32 v156, v181
	v_mov_b32_e32 v157, v182
	v_mov_b32_e32 v181, v183
	v_pk_mul_f32 v[122:123], v[122:123], v[0:1] op_sel_hi:[1,0]
	v_fmamk_f32 v140, v140, 0x3a800000, v222
	v_pk_add_f32 v[156:157], v[156:157], v[180:181]
	v_pk_mul_f32 v[122:123], v[130:131], v[122:123]
	v_add_f32_e32 v130, 1.0, v151
	v_rsq_f32_e32 v142, v140
	v_add_f32_e32 v140, v156, v157
	v_add_f32_e32 v147, 1.0, v147
	v_rcp_f32_e32 v157, v130
	v_pk_mul_f32 v[130:131], v[132:133], v[0:1] op_sel_hi:[1,0]
	v_pk_mul_f32 v[126:127], v[126:127], v[0:1] op_sel_hi:[1,0]
	v_pk_mul_f32 v[124:125], v[124:125], v[0:1] op_sel_hi:[1,0]
	v_pk_mul_f32 v[118:119], v[118:119], v[0:1] op_sel_hi:[1,0]
	v_rcp_f32_e32 v156, v147
	v_mul_f32_e32 v133, 0xbfb8aa3b, v131
	v_mul_f32_e32 v147, 0xbfb8aa3b, v126
	v_pk_mul_f32 v[124:125], v[130:131], v[124:125]
	v_mul_f32_e32 v131, 0xbfb8aa3b, v127
	v_pk_mul_f32 v[118:119], v[126:127], v[118:119]
	v_pk_mul_f32 v[126:127], v[128:129], v[0:1] op_sel_hi:[1,0]
	v_mul_f32_e32 v132, 0xbfb8aa3b, v130
	v_mul_f32_e32 v128, 0xbfb8aa3b, v126
	v_mul_f32_e32 v129, 0xbfb8aa3b, v127
	v_exp_f32_e32 v132, v132
	v_exp_f32_e32 v133, v133
	v_exp_f32_e32 v147, v147
	v_exp_f32_e32 v131, v131
	v_exp_f32_e32 v128, v128
	v_exp_f32_e32 v129, v129
	v_add_f32_e32 v132, 1.0, v132
	v_add_f32_e32 v133, 1.0, v133
	v_add_f32_e32 v130, 1.0, v147
	v_add_f32_e32 v131, 1.0, v131
	v_add_f32_e32 v128, 1.0, v128
	v_add_f32_e32 v129, 1.0, v129
	v_rcp_f32_e32 v132, v132
	v_rcp_f32_e32 v133, v133
	v_rcp_f32_e32 v130, v130
	v_rcp_f32_e32 v131, v131
	v_rcp_f32_e32 v128, v128
	v_rcp_f32_e32 v129, v129
	s_mul_hi_i32 s39, s21, 0x1414000
	s_mul_i32 s21, s21, 0x1414000
	v_bitop3_b32 v149, s19, v230, v97 bitop3:0xc8
	v_pk_mul_f32 v[120:121], v[120:121], v[0:1] op_sel_hi:[1,0]
	s_add_u32 s38, s4, s21
	v_pk_mul_f32 v[120:121], v[126:127], v[120:121]
	v_mul_u32_u24_e32 v0, 0xb00, v149
	v_ashrrev_i32_e32 v185, 31, v184
	v_pk_mul_f32 v[122:123], v[122:123], v[156:157]
	v_pk_mul_f32 v[124:125], v[124:125], v[132:133]
	v_pk_mul_f32 v[118:119], v[118:119], v[130:131]
	v_pk_mul_f32 v[126:127], v[120:121], v[128:129]
	s_addc_u32 s39, s5, s39
	v_lshlrev_b32_e32 v0, 1, v0
	v_cvt_pk_bf16_f32 v120, v122, v123
	v_cvt_pk_bf16_f32 v121, v124, v125
	v_cvt_pk_bf16_f32 v122, v118, v119
	v_cvt_pk_bf16_f32 v123, v126, v127
	v_lshl_add_u64 v[124:125], s[38:39], 0, v[0:1]
	v_lshlrev_b64 v[118:119], 1, v[184:185]
	v_pk_mul_f32 v[126:127], v[114:115], v[154:155] op_sel_hi:[1,0]
	v_lshl_add_u64 v[114:115], v[124:125], 0, v[118:119]
	v_mul_f32_e32 v0, 0xbfb8aa3b, v126
	v_exp_f32_e32 v0, v0
	s_cmp_eq_u32 s32, 1
	s_cbranch_scc1 .Lup_st0
	flat_store_dwordx4 v[114:115], v[120:123]
.Lup_st0:
	v_pk_mul_f32 v[116:117], v[116:117], v[154:155] op_sel_hi:[1,0]
	v_pk_mul_f32 v[106:107], v[106:107], v[154:155] op_sel_hi:[1,0]
	v_mul_f32_e32 v120, 0xbfb8aa3b, v127
	v_exp_f32_e32 v121, v120
	v_add_f32_e32 v0, 1.0, v0
	v_rcp_f32_e32 v120, v0
	v_mul_f32_e32 v122, 0xbfb8aa3b, v117
	v_add_f32_e32 v0, 1.0, v121
	v_rcp_f32_e32 v121, v0
	v_mul_f32_e32 v0, 0xbfb8aa3b, v116
	v_exp_f32_e32 v0, v0
	v_exp_f32_e32 v122, v122
	v_pk_mul_f32 v[106:107], v[126:127], v[106:107]
	v_pk_mul_f32 v[110:111], v[110:111], v[154:155] op_sel_hi:[1,0]
	v_add_f32_e32 v0, 1.0, v0
	v_pk_mul_f32 v[106:107], v[106:107], v[120:121]
	v_rcp_f32_e32 v120, v0
	v_add_f32_e32 v0, 1.0, v122
	v_rcp_f32_e32 v121, v0
	v_mul_f32_e32 v0, 0xbfb8aa3b, v110
	v_pk_mul_f32 v[108:109], v[108:109], v[154:155] op_sel_hi:[1,0]
	v_pk_mul_f32 v[102:103], v[102:103], v[154:155] op_sel_hi:[1,0]
	v_exp_f32_e32 v0, v0
	v_pk_mul_f32 v[108:109], v[116:117], v[108:109]
	v_mul_f32_e32 v116, 0xbfb8aa3b, v111
	v_pk_mul_f32 v[102:103], v[110:111], v[102:103]
	v_pk_mul_f32 v[110:111], v[112:113], v[154:155] op_sel_hi:[1,0]
	v_exp_f32_e32 v117, v116
	v_mul_f32_e32 v112, 0xbfb8aa3b, v110
	v_exp_f32_e32 v112, v112
	v_mul_f32_e32 v113, 0xbfb8aa3b, v111
	v_exp_f32_e32 v113, v113
	v_add_f32_e32 v0, 1.0, v0
	v_rcp_f32_e32 v116, v0
	v_add_f32_e32 v0, 1.0, v117
	v_rcp_f32_e32 v117, v0
	v_add_f32_e32 v0, 1.0, v112
	v_rcp_f32_e32 v112, v0
	v_add_f32_e32 v0, 1.0, v113
	v_rcp_f32_e32 v113, v0
	v_pk_mul_f32 v[116:117], v[102:103], v[116:117]
	v_pk_mul_f32 v[102:103], v[104:105], v[154:155] op_sel_hi:[1,0]
	s_mov_b32 s21, 0x16000
	v_pk_mul_f32 v[102:103], v[110:111], v[102:103]
	v_pk_mul_f32 v[108:109], v[108:109], v[120:121]
	v_pk_mul_f32 v[110:111], v[102:103], v[112:113]
	v_cvt_pk_bf16_f32 v102, v106, v107
	v_pk_mul_f32 v[98:99], v[98:99], v[152:153] op_sel_hi:[1,0]
	v_add_co_u32_e32 v106, vcc, s21, v114
	v_cvt_pk_bf16_f32 v103, v108, v109
	v_cvt_pk_bf16_f32 v104, v116, v117
	v_cvt_pk_bf16_f32 v105, v110, v111
	v_mul_f32_e32 v0, 0xbfb8aa3b, v98
	v_addc_co_u32_e32 v107, vcc, 0, v115, vcc
	v_exp_f32_e32 v0, v0
	s_cmp_eq_u32 s32, 1
	s_cbranch_scc1 .Lup_st1
	flat_store_dwordx4 v[106:107], v[102:105]
.Lup_st1:
	v_pk_mul_f32 v[86:87], v[86:87], v[152:153] op_sel_hi:[1,0]
	v_pk_mul_f32 v[90:91], v[90:91], v[152:153] op_sel_hi:[1,0]
	v_mul_f32_e32 v102, 0xbfb8aa3b, v99
	v_exp_f32_e32 v103, v102
	v_add_f32_e32 v0, 1.0, v0
	v_rcp_f32_e32 v102, v0
	v_pk_mul_f32 v[86:87], v[98:99], v[86:87]
	v_add_f32_e32 v0, 1.0, v103
	v_pk_mul_f32 v[98:99], v[100:101], v[152:153] op_sel_hi:[1,0]
	v_rcp_f32_e32 v103, v0
	v_mul_f32_e32 v0, 0xbfb8aa3b, v98
	v_exp_f32_e32 v0, v0
	v_mul_f32_e32 v100, 0xbfb8aa3b, v99
	v_exp_f32_e32 v101, v100
	v_pk_mul_f32 v[88:89], v[88:89], v[152:153] op_sel_hi:[1,0]
	v_add_f32_e32 v0, 1.0, v0
	v_rcp_f32_e32 v100, v0
	v_add_f32_e32 v0, 1.0, v101
	v_rcp_f32_e32 v101, v0
	v_mul_f32_e32 v0, 0xbfb8aa3b, v90
	v_pk_mul_f32 v[82:83], v[82:83], v[152:153] op_sel_hi:[1,0]
	v_exp_f32_e32 v0, v0
	v_pk_mul_f32 v[88:89], v[98:99], v[88:89]
	v_mul_f32_e32 v98, 0xbfb8aa3b, v91
	v_pk_mul_f32 v[82:83], v[90:91], v[82:83]
	v_pk_mul_f32 v[90:91], v[92:93], v[152:153] op_sel_hi:[1,0]
	v_exp_f32_e32 v99, v98
	v_mul_f32_e32 v92, 0xbfb8aa3b, v90
	v_exp_f32_e32 v92, v92
	v_mul_f32_e32 v93, 0xbfb8aa3b, v91
	v_exp_f32_e32 v93, v93
	v_add_f32_e32 v0, 1.0, v0
	v_rcp_f32_e32 v98, v0
	v_add_f32_e32 v0, 1.0, v99
	v_rcp_f32_e32 v99, v0
	v_add_f32_e32 v0, 1.0, v92
	v_rcp_f32_e32 v92, v0
	v_add_f32_e32 v0, 1.0, v93
	v_rcp_f32_e32 v93, v0
	v_pk_mul_f32 v[98:99], v[82:83], v[98:99]
	v_pk_mul_f32 v[82:83], v[84:85], v[152:153] op_sel_hi:[1,0]
	v_pk_mul_f32 v[86:87], v[86:87], v[102:103]
	v_pk_mul_f32 v[82:83], v[90:91], v[82:83]
	s_mov_b32 s40, 0x2c000
	v_pk_mul_f32 v[88:89], v[88:89], v[100:101]
	v_pk_mul_f32 v[90:91], v[82:83], v[92:93]
	v_cvt_pk_bf16_f32 v82, v86, v87
	v_pk_mul_f32 v[78:79], v[78:79], v[150:151] op_sel_hi:[1,0]
	v_add_co_u32_e32 v86, vcc, s40, v114
	v_cvt_pk_bf16_f32 v83, v88, v89
	v_cvt_pk_bf16_f32 v84, v98, v99
	v_cvt_pk_bf16_f32 v85, v90, v91
	v_mul_f32_e32 v0, 0xbfb8aa3b, v78
	v_addc_co_u32_e32 v87, vcc, 0, v115, vcc
	v_exp_f32_e32 v0, v0
	s_cmp_eq_u32 s32, 1
	s_cbranch_scc1 .Lup_st2
	flat_store_dwordx4 v[86:87], v[82:85]
.Lup_st2:
	v_pk_mul_f32 v[70:71], v[70:71], v[150:151] op_sel_hi:[1,0]
	v_pk_mul_f32 v[74:75], v[74:75], v[150:151] op_sel_hi:[1,0]
	v_mul_f32_e32 v82, 0xbfb8aa3b, v79
	v_exp_f32_e32 v83, v82
	v_add_f32_e32 v0, 1.0, v0
	v_rcp_f32_e32 v82, v0
	v_pk_mul_f32 v[70:71], v[78:79], v[70:71]
	v_add_f32_e32 v0, 1.0, v83
	v_pk_mul_f32 v[78:79], v[80:81], v[150:151] op_sel_hi:[1,0]
	v_rcp_f32_e32 v83, v0
	v_mul_f32_e32 v0, 0xbfb8aa3b, v78
	v_exp_f32_e32 v0, v0
	v_mul_f32_e32 v80, 0xbfb8aa3b, v79
	v_exp_f32_e32 v81, v80
	v_pk_mul_f32 v[72:73], v[72:73], v[150:151] op_sel_hi:[1,0]
	v_add_f32_e32 v0, 1.0, v0
	v_rcp_f32_e32 v80, v0
	v_add_f32_e32 v0, 1.0, v81
	v_rcp_f32_e32 v81, v0
	v_mul_f32_e32 v0, 0xbfb8aa3b, v74
	v_pk_mul_f32 v[66:67], v[66:67], v[150:151] op_sel_hi:[1,0]
	v_exp_f32_e32 v0, v0
	v_pk_mul_f32 v[72:73], v[78:79], v[72:73]
	v_mul_f32_e32 v78, 0xbfb8aa3b, v75
	v_pk_mul_f32 v[66:67], v[74:75], v[66:67]
	v_pk_mul_f32 v[74:75], v[76:77], v[150:151] op_sel_hi:[1,0]
	v_exp_f32_e32 v79, v78
	v_mul_f32_e32 v76, 0xbfb8aa3b, v74
	v_exp_f32_e32 v76, v76
	v_mul_f32_e32 v77, 0xbfb8aa3b, v75
	v_exp_f32_e32 v77, v77
	v_add_f32_e32 v0, 1.0, v0
	v_rcp_f32_e32 v78, v0
	v_add_f32_e32 v0, 1.0, v79
	v_rcp_f32_e32 v79, v0
	v_add_f32_e32 v0, 1.0, v76
	v_rcp_f32_e32 v76, v0
	v_add_f32_e32 v0, 1.0, v77
	v_rcp_f32_e32 v77, v0
	v_pk_mul_f32 v[78:79], v[66:67], v[78:79]
	v_pk_mul_f32 v[66:67], v[68:69], v[150:151] op_sel_hi:[1,0]
	v_pk_mul_f32 v[70:71], v[70:71], v[82:83]
	v_pk_mul_f32 v[66:67], v[74:75], v[66:67]
	s_mov_b32 s19, 0x42000
	v_pk_mul_f32 v[72:73], v[72:73], v[80:81]
	v_pk_mul_f32 v[74:75], v[66:67], v[76:77]
	v_cvt_pk_bf16_f32 v66, v70, v71
	v_add_co_u32_e32 v70, vcc, s19, v114
	v_pk_mul_f32 v[62:63], v[62:63], v[146:147] op_sel_hi:[1,0]
	v_cvt_pk_bf16_f32 v67, v72, v73
	v_cvt_pk_bf16_f32 v68, v78, v79
	v_cvt_pk_bf16_f32 v69, v74, v75
	v_addc_co_u32_e32 v71, vcc, 0, v115, vcc
	v_mul_f32_e32 v0, 0xbfb8aa3b, v62
	s_cmp_eq_u32 s32, 1
	s_cbranch_scc1 .Lup_st3
	flat_store_dwordx4 v[70:71], v[66:69]
.Lup_st3:
	v_exp_f32_e32 v0, v0
	v_pk_mul_f32 v[54:55], v[54:55], v[146:147] op_sel_hi:[1,0]
	v_mul_f32_e32 v66, 0xbfb8aa3b, v63
	v_exp_f32_e32 v67, v66
	v_add_f32_e32 v0, 1.0, v0
	v_rcp_f32_e32 v66, v0
	v_pk_mul_f32 v[54:55], v[62:63], v[54:55]
	v_add_f32_e32 v0, 1.0, v67
	v_pk_mul_f32 v[62:63], v[64:65], v[146:147] op_sel_hi:[1,0]
	v_rcp_f32_e32 v67, v0
	v_mul_f32_e32 v0, 0xbfb8aa3b, v62
	v_exp_f32_e32 v0, v0
	v_mul_f32_e32 v64, 0xbfb8aa3b, v63
	v_exp_f32_e32 v65, v64
	v_pk_mul_f32 v[58:59], v[58:59], v[146:147] op_sel_hi:[1,0]
	v_add_f32_e32 v0, 1.0, v0
	v_rcp_f32_e32 v64, v0
	v_add_f32_e32 v0, 1.0, v65
	v_rcp_f32_e32 v65, v0
	v_mul_f32_e32 v0, 0xbfb8aa3b, v58
	v_pk_mul_f32 v[56:57], v[56:57], v[146:147] op_sel_hi:[1,0]
	v_pk_mul_f32 v[50:51], v[50:51], v[146:147] op_sel_hi:[1,0]
	v_exp_f32_e32 v0, v0
	v_pk_mul_f32 v[56:57], v[62:63], v[56:57]
	v_mul_f32_e32 v62, 0xbfb8aa3b, v59
	v_pk_mul_f32 v[50:51], v[58:59], v[50:51]
	v_pk_mul_f32 v[58:59], v[60:61], v[146:147] op_sel_hi:[1,0]
	v_exp_f32_e32 v63, v62
	v_mul_f32_e32 v60, 0xbfb8aa3b, v58
	v_exp_f32_e32 v60, v60
	v_mul_f32_e32 v61, 0xbfb8aa3b, v59
	v_exp_f32_e32 v61, v61
	v_add_f32_e32 v0, 1.0, v0
	v_rcp_f32_e32 v62, v0
	v_add_f32_e32 v0, 1.0, v63
	v_rcp_f32_e32 v63, v0
	v_add_f32_e32 v0, 1.0, v60
	v_rcp_f32_e32 v60, v0
	v_add_f32_e32 v0, 1.0, v61
	v_rcp_f32_e32 v61, v0
	v_pk_mul_f32 v[62:63], v[50:51], v[62:63]
	v_pk_mul_f32 v[50:51], v[52:53], v[146:147] op_sel_hi:[1,0]
	v_and_b32_e32 v69, 0x7cf, v148
	v_pk_mul_f32 v[54:55], v[54:55], v[66:67]
	v_pk_mul_f32 v[50:51], v[58:59], v[50:51]
	v_ashrrev_i32_e32 v68, 11, v148
	v_pk_mul_f32 v[58:59], v[50:51], v[60:61]
	v_cvt_pk_bf16_f32 v50, v54, v55
	v_mov_b64_e32 v[54:55], s[4:5]
	s_mov_b32 s19, 0x1414000
	v_mul_u32_u24_e32 v0, 0xb00, v69
	v_pk_mul_f32 v[56:57], v[56:57], v[64:65]
	v_mad_i64_i32 v[54:55], s[38:39], v68, s19, v[54:55]
	v_lshlrev_b32_e32 v0, 1, v0
	v_cvt_pk_bf16_f32 v51, v56, v57
	v_lshl_add_u64 v[54:55], v[54:55], 0, v[0:1]
	v_pk_mul_f32 v[56:57], v[46:47], v[144:145] op_sel_hi:[1,0]
	v_cvt_pk_bf16_f32 v52, v62, v63
	v_cvt_pk_bf16_f32 v53, v58, v59
	v_mul_f32_e32 v0, 0xbfb8aa3b, v56
	v_lshl_add_u64 v[46:47], v[54:55], 0, v[118:119]
	v_exp_f32_e32 v0, v0
	s_cmp_eq_u32 s32, 2
	s_cbranch_scc1 .Lup_st4
	flat_store_dwordx4 v[46:47], v[50:53]
.Lup_st4:
	v_pk_mul_f32 v[48:49], v[48:49], v[144:145] op_sel_hi:[1,0]
	v_pk_mul_f32 v[38:39], v[38:39], v[144:145] op_sel_hi:[1,0]
	v_mul_f32_e32 v50, 0xbfb8aa3b, v57
	v_exp_f32_e32 v51, v50
	v_add_f32_e32 v0, 1.0, v0
	v_rcp_f32_e32 v50, v0
	v_mul_f32_e32 v52, 0xbfb8aa3b, v49
	v_add_f32_e32 v0, 1.0, v51
	v_rcp_f32_e32 v51, v0
	v_mul_f32_e32 v0, 0xbfb8aa3b, v48
	v_exp_f32_e32 v0, v0
	v_exp_f32_e32 v52, v52
	v_pk_mul_f32 v[38:39], v[56:57], v[38:39]
	v_pk_mul_f32 v[42:43], v[42:43], v[144:145] op_sel_hi:[1,0]
	v_add_f32_e32 v0, 1.0, v0
	v_pk_mul_f32 v[38:39], v[38:39], v[50:51]
	v_rcp_f32_e32 v50, v0
	v_add_f32_e32 v0, 1.0, v52
	v_rcp_f32_e32 v51, v0
	v_mul_f32_e32 v0, 0xbfb8aa3b, v42
	v_pk_mul_f32 v[40:41], v[40:41], v[144:145] op_sel_hi:[1,0]
	v_pk_mul_f32 v[34:35], v[34:35], v[144:145] op_sel_hi:[1,0]
	v_exp_f32_e32 v0, v0
	v_pk_mul_f32 v[40:41], v[48:49], v[40:41]
	v_mul_f32_e32 v48, 0xbfb8aa3b, v43
	v_pk_mul_f32 v[34:35], v[42:43], v[34:35]
	v_pk_mul_f32 v[42:43], v[44:45], v[144:145] op_sel_hi:[1,0]
	v_exp_f32_e32 v49, v48
	v_mul_f32_e32 v44, 0xbfb8aa3b, v42
	v_exp_f32_e32 v44, v44
	v_mul_f32_e32 v45, 0xbfb8aa3b, v43
	v_exp_f32_e32 v45, v45
	v_add_f32_e32 v0, 1.0, v0
	v_rcp_f32_e32 v48, v0
	v_add_f32_e32 v0, 1.0, v49
	v_rcp_f32_e32 v49, v0
	v_add_f32_e32 v0, 1.0, v44
	v_rcp_f32_e32 v44, v0
	v_add_f32_e32 v0, 1.0, v45
	v_rcp_f32_e32 v45, v0
	v_pk_mul_f32 v[48:49], v[34:35], v[48:49]
	v_pk_mul_f32 v[34:35], v[36:37], v[144:145] op_sel_hi:[1,0]
	v_pk_mul_f32 v[40:41], v[40:41], v[50:51]
	v_pk_mul_f32 v[34:35], v[42:43], v[34:35]
	v_pk_mul_f32 v[30:31], v[30:31], v[142:143] op_sel_hi:[1,0]
	v_pk_mul_f32 v[42:43], v[34:35], v[44:45]
	v_cvt_pk_bf16_f32 v34, v38, v39
	v_add_co_u32_e32 v38, vcc, s21, v46
	v_cvt_pk_bf16_f32 v35, v40, v41
	v_cvt_pk_bf16_f32 v36, v48, v49
	v_cvt_pk_bf16_f32 v37, v42, v43
	v_mul_f32_e32 v0, 0xbfb8aa3b, v30
	v_addc_co_u32_e32 v39, vcc, 0, v47, vcc
	v_exp_f32_e32 v0, v0
	s_cmp_eq_u32 s32, 2
	s_cbranch_scc1 .Lup_st5
	flat_store_dwordx4 v[38:39], v[34:37]
.Lup_st5:
	v_pk_mul_f32 v[22:23], v[22:23], v[142:143] op_sel_hi:[1,0]
	v_pk_mul_f32 v[26:27], v[26:27], v[142:143] op_sel_hi:[1,0]
	v_mul_f32_e32 v34, 0xbfb8aa3b, v31
	v_exp_f32_e32 v35, v34
	v_add_f32_e32 v0, 1.0, v0
	v_rcp_f32_e32 v34, v0
	v_pk_mul_f32 v[22:23], v[30:31], v[22:23]
	v_add_f32_e32 v0, 1.0, v35
	v_pk_mul_f32 v[30:31], v[32:33], v[142:143] op_sel_hi:[1,0]
	v_rcp_f32_e32 v35, v0
	v_mul_f32_e32 v0, 0xbfb8aa3b, v30
	v_exp_f32_e32 v0, v0
	v_mul_f32_e32 v32, 0xbfb8aa3b, v31
	v_exp_f32_e32 v33, v32
	v_pk_mul_f32 v[24:25], v[24:25], v[142:143] op_sel_hi:[1,0]
	v_add_f32_e32 v0, 1.0, v0
	v_rcp_f32_e32 v32, v0
	v_add_f32_e32 v0, 1.0, v33
	v_rcp_f32_e32 v33, v0
	v_mul_f32_e32 v0, 0xbfb8aa3b, v26
	v_pk_mul_f32 v[18:19], v[18:19], v[142:143] op_sel_hi:[1,0]
	v_exp_f32_e32 v0, v0
	v_pk_mul_f32 v[24:25], v[30:31], v[24:25]
	v_mul_f32_e32 v30, 0xbfb8aa3b, v27
	v_pk_mul_f32 v[18:19], v[26:27], v[18:19]
	v_pk_mul_f32 v[26:27], v[28:29], v[142:143] op_sel_hi:[1,0]
	v_exp_f32_e32 v31, v30
	v_mul_f32_e32 v28, 0xbfb8aa3b, v26
	v_exp_f32_e32 v28, v28
	v_mul_f32_e32 v29, 0xbfb8aa3b, v27
	v_exp_f32_e32 v29, v29
	v_add_f32_e32 v0, 1.0, v0
	v_rcp_f32_e32 v30, v0
	v_add_f32_e32 v0, 1.0, v31
	v_rcp_f32_e32 v31, v0
	v_add_f32_e32 v0, 1.0, v28
	v_fmamk_f32 v140, v140, 0x3a800000, v222
	v_rcp_f32_e32 v28, v0
	v_add_f32_e32 v0, 1.0, v29
	v_rsq_f32_e32 v140, v140
	v_rcp_f32_e32 v29, v0
	v_pk_mul_f32 v[30:31], v[18:19], v[30:31]
	v_pk_mul_f32 v[18:19], v[20:21], v[142:143] op_sel_hi:[1,0]
	v_pk_mul_f32 v[22:23], v[22:23], v[34:35]
	v_pk_mul_f32 v[18:19], v[26:27], v[18:19]
	v_pk_mul_f32 v[24:25], v[24:25], v[32:33]
	v_pk_mul_f32 v[26:27], v[18:19], v[28:29]
	v_cvt_pk_bf16_f32 v18, v22, v23
	v_pk_mul_f32 v[14:15], v[14:15], v[140:141] op_sel_hi:[1,0]
	v_add_co_u32_e32 v22, vcc, s40, v46
	v_cvt_pk_bf16_f32 v19, v24, v25
	v_cvt_pk_bf16_f32 v20, v30, v31
	v_cvt_pk_bf16_f32 v21, v26, v27
	v_mul_f32_e32 v0, 0xbfb8aa3b, v14
	v_addc_co_u32_e32 v23, vcc, 0, v47, vcc
	v_exp_f32_e32 v0, v0
	s_cmp_eq_u32 s32, 2
	s_cbranch_scc1 .Lup_st6
	flat_store_dwordx4 v[22:23], v[18:21]
.Lup_st6:
	v_pk_mul_f32 v[6:7], v[6:7], v[140:141] op_sel_hi:[1,0]
	v_pk_mul_f32 v[10:11], v[10:11], v[140:141] op_sel_hi:[1,0]
	v_mul_f32_e32 v18, 0xbfb8aa3b, v15
	v_exp_f32_e32 v19, v18
	v_add_f32_e32 v0, 1.0, v0
	v_rcp_f32_e32 v18, v0
	v_pk_mul_f32 v[6:7], v[14:15], v[6:7]
	v_add_f32_e32 v0, 1.0, v19
	v_pk_mul_f32 v[14:15], v[16:17], v[140:141] op_sel_hi:[1,0]
	v_rcp_f32_e32 v19, v0
	v_mul_f32_e32 v0, 0xbfb8aa3b, v14
	v_exp_f32_e32 v0, v0
	v_mul_f32_e32 v16, 0xbfb8aa3b, v15
	v_exp_f32_e32 v17, v16
	v_pk_mul_f32 v[8:9], v[8:9], v[140:141] op_sel_hi:[1,0]
	v_add_f32_e32 v0, 1.0, v0
	v_rcp_f32_e32 v16, v0
	v_add_f32_e32 v0, 1.0, v17
	v_rcp_f32_e32 v17, v0
	v_mul_f32_e32 v0, 0xbfb8aa3b, v10
	v_pk_mul_f32 v[2:3], v[2:3], v[140:141] op_sel_hi:[1,0]
	v_exp_f32_e32 v0, v0
	v_pk_mul_f32 v[8:9], v[14:15], v[8:9]
	v_mul_f32_e32 v14, 0xbfb8aa3b, v11
	v_pk_mul_f32 v[2:3], v[10:11], v[2:3]
	v_pk_mul_f32 v[10:11], v[12:13], v[140:141] op_sel_hi:[1,0]
	v_exp_f32_e32 v15, v14
	v_mul_f32_e32 v12, 0xbfb8aa3b, v10
	v_exp_f32_e32 v12, v12
	v_mul_f32_e32 v13, 0xbfb8aa3b, v11
	v_exp_f32_e32 v13, v13
	v_add_f32_e32 v0, 1.0, v0
	v_rcp_f32_e32 v14, v0
	v_add_f32_e32 v0, 1.0, v15
	v_rcp_f32_e32 v15, v0
	v_add_f32_e32 v0, 1.0, v12
	v_rcp_f32_e32 v12, v0
	v_add_f32_e32 v0, 1.0, v13
	v_rcp_f32_e32 v13, v0
	v_pk_mul_f32 v[14:15], v[2:3], v[14:15]
	v_pk_mul_f32 v[2:3], v[4:5], v[140:141] op_sel_hi:[1,0]
	v_pk_mul_f32 v[6:7], v[6:7], v[18:19]
	v_pk_mul_f32 v[2:3], v[10:11], v[2:3]
	v_pk_mul_f32 v[8:9], v[8:9], v[16:17]
	v_pk_mul_f32 v[10:11], v[2:3], v[12:13]
	v_cvt_pk_bf16_f32 v2, v6, v7
	v_add_co_u32_e32 v6, vcc, 0x42000, v46
	v_cvt_pk_bf16_f32 v3, v8, v9
	v_cvt_pk_bf16_f32 v4, v14, v15
	v_cvt_pk_bf16_f32 v5, v10, v11
	v_addc_co_u32_e32 v7, vcc, 0, v47, vcc
	s_cmp_eq_u32 s32, 2
	s_cbranch_scc1 .Lup_st7
	flat_store_dwordx4 v[6:7], v[2:5]
.Lup_st7:
	s_andn2_b64 vcc, exec, s[36:37]
	s_mov_b64 s[36:37], -1
	s_cbranch_vccnz .LBB0_561
	s_andn2_b64 vcc, exec, s[0:1]
	s_cbranch_vccnz .LBB0_560
	s_barrier
	s_branch .LBB0_560
